# stack of small edits: no entry barrier in the attention and state tiles (it follows the queue hand-out barriers), half-wave exchange address hoisted out of the K-tile loop, tile position updated in pl
# baseline (speedup 1.0000x reference)
.LBB0_1272:
	v_mov_b32_e32 v121, v252
	s_waitcnt vmcnt(63) expcnt(7) lgkmcnt(15)
	s_load_dwordx2 s[4:5], s[0:1], 0x60
	s_add_i32 s9, s18, 0xfffffdd9
	v_readfirstlane_b32 s8, v121
	v_and_b32_e32 v140, 63, v121
	s_ashr_i32 s30, s8, 6
	s_lshl_b32 s10, s9, 6
	v_or_b32_e32 v0, s10, v140
	s_ashr_i32 s31, s30, 31
	v_lshlrev_b64 v[2:3], 5, v[0:1]
	s_lshl_b64 s[2:3], s[30:31], 2
	v_lshl_add_u64 v[2:3], s[12:13], 0, v[2:3]
	s_waitcnt lgkmcnt(0)
	s_add_u32 s4, s4, s2
	v_lshl_add_u64 v[2:3], v[2:3], 0, s[2:3]
	s_addc_u32 s5, s5, s3
	global_load_dword v0, v[2:3], off
	s_nop 0
	global_load_dword v2, v1, s[4:5]
	s_mov_b32 s4, 0x41a00000
	s_waitcnt vmcnt(0)
	v_add_f32_e32 v0, v0, v2
	v_cmp_nlt_f32_e32 vcc, s4, v0
	s_and_saveexec_b64 s[4:5], vcc
	s_cbranch_execz .LBB0_1274
	v_mul_f32_e32 v2, 0x3fb8aa3b, v0
	v_rndne_f32_e32 v3, v2
	s_mov_b32 s6, 0x3fb8aa3b
	v_sub_f32_e32 v4, v2, v3
	v_fma_f32 v2, v0, s6, -v2
	v_fmac_f32_e32 v2, 0x32a5705f, v0
	v_add_f32_e32 v2, v4, v2
	v_cvt_i32_f32_e32 v3, v3
	v_exp_f32_e32 v2, v2
	s_mov_b32 s6, 0xc2ce8ed0
	v_cmp_ngt_f32_e32 vcc, s6, v0
	s_mov_b32 s6, 0x3f2aaaab
	v_ldexp_f32 v2, v2, v3
	v_cndmask_b32_e32 v2, 0, v2, vcc
	v_cmp_nlt_f32_e32 vcc, s80, v0
	s_nop 1
	v_cndmask_b32_e32 v0, v183, v2, vcc
	v_add_f32_e32 v4, 1.0, v0
	v_add_f32_e32 v2, -1.0, v4
	v_sub_f32_e32 v3, v2, v4
	v_add_f32_e32 v3, 1.0, v3
	v_sub_f32_e32 v2, v0, v2
	v_add_f32_e32 v5, v2, v3
	v_frexp_mant_f32_e32 v6, v4
	v_cvt_f64_f32_e32 v[2:3], v4
	v_frexp_exp_i32_f64_e32 v2, v[2:3]
	v_cmp_gt_f32_e32 vcc, s6, v6
	s_mov_b32 s6, 0x3f317218
	s_nop 0
	v_subbrev_co_u32_e32 v10, vcc, 0, v2, vcc
	v_sub_u32_e32 v2, 0, v10
	v_ldexp_f32 v3, v4, v2
	v_add_f32_e32 v4, -1.0, v3
	v_add_f32_e32 v6, 1.0, v3
	v_ldexp_f32 v2, v5, v2
	v_add_f32_e32 v5, 1.0, v4
	v_add_f32_e32 v7, -1.0, v6
	v_sub_f32_e32 v5, v3, v5
	v_sub_f32_e32 v3, v3, v7
	v_add_f32_e32 v5, v2, v5
	v_add_f32_e32 v2, v2, v3
	v_add_f32_e32 v11, v6, v2
	v_rcp_f32_e32 v13, v11
	v_sub_f32_e32 v3, v6, v11
	v_add_f32_e32 v12, v2, v3
	v_add_f32_e32 v3, v4, v5
	v_mul_f32_e32 v15, v3, v13
	v_sub_f32_e32 v2, v4, v3
	v_mul_f32_e32 v4, v11, v15
	v_fma_f32 v6, v15, v11, -v4
	v_fmac_f32_e32 v6, v15, v12
	v_add_f32_e32 v14, v5, v2
	v_add_f32_e32 v2, v4, v6
	v_sub_f32_e32 v5, v3, v2
	v_pk_add_f32 v[8:9], v[2:3], v[4:5] neg_lo:[0,1] neg_hi:[0,1]
	v_mov_b32_e32 v7, v2
	v_pk_add_f32 v[2:3], v[8:9], v[6:7] neg_lo:[0,1] neg_hi:[0,1]
	s_nop 0
	v_add_f32_e32 v3, v14, v3
	v_add_f32_e32 v2, v2, v3
	v_add_f32_e32 v3, v5, v2
	v_mul_f32_e32 v14, v13, v3
	v_mul_f32_e32 v4, v11, v14
	v_fma_f32 v6, v14, v11, -v4
	v_fmac_f32_e32 v6, v14, v12
	v_sub_f32_e32 v5, v5, v3
	v_add_f32_e32 v11, v2, v5
	v_add_f32_e32 v2, v4, v6
	v_sub_f32_e32 v5, v3, v2
	v_pk_add_f32 v[8:9], v[2:3], v[4:5] neg_lo:[0,1] neg_hi:[0,1]
	v_mov_b32_e32 v7, v2
	v_pk_add_f32 v[2:3], v[8:9], v[6:7] neg_lo:[0,1] neg_hi:[0,1]
	s_nop 0
	v_add_f32_e32 v3, v11, v3
	v_add_f32_e32 v2, v2, v3
	v_add_f32_e32 v3, v15, v14
	v_add_f32_e32 v2, v5, v2
	v_sub_f32_e32 v4, v3, v15
	v_mul_f32_e32 v2, v13, v2
	v_sub_f32_e32 v4, v14, v4
	v_add_f32_e32 v4, v4, v2
	v_add_f32_e32 v6, v3, v4
	v_mul_f32_e32 v7, v6, v6
	v_fmamk_f32 v2, v7, 0x3e9b6dac, v178
	v_fmaak_f32 v165, v7, v2, 0x3f2aaada
	v_cvt_f32_i32_e32 v2, v10
	v_sub_f32_e32 v3, v6, v3
	v_sub_f32_e32 v3, v4, v3
	v_ldexp_f32 v8, v3, 1
	v_mul_f32_e32 v3, v6, v7
	v_ldexp_f32 v5, v6, 1
	v_pk_mul_f32 v[6:7], v[2:3], v[164:165]
	s_nop 0
	v_fma_f32 v4, v2, s6, -v6
	v_fmac_f32_e32 v4, 0xb102e308, v2
	v_pk_add_f32 v[2:3], v[6:7], v[4:5]
	s_mov_b32 s6, 0x7f800000
	v_sub_f32_e32 v5, v3, v5
	v_sub_f32_e32 v5, v7, v5
	v_add_f32_e32 v9, v8, v5
	v_mov_b32_e32 v8, v6
	v_pk_add_f32 v[6:7], v[2:3], v[6:7] neg_lo:[0,1] neg_hi:[0,1]
	v_pk_add_f32 v[10:11], v[2:3], v[8:9]
	v_mov_b32_e32 v5, v2
	v_mov_b32_e32 v7, v11
	v_pk_add_f32 v[12:13], v[4:5], v[6:7] neg_lo:[0,1] neg_hi:[0,1]
	v_pk_add_f32 v[4:5], v[4:5], v[6:7]
	v_mov_b32_e32 v8, v9
	v_pk_add_f32 v[6:7], v[4:5], v[2:3] op_sel:[1,0] op_sel_hi:[0,1] neg_lo:[0,1] neg_hi:[0,1]
	v_pk_add_f32 v[14:15], v[10:11], v[6:7] op_sel_hi:[1,0] neg_lo:[0,1] neg_hi:[0,1]
	v_mov_b32_e32 v10, v11
	v_mov_b32_e32 v11, v5
	v_pk_mov_b32 v[6:7], v[2:3], v[6:7] op_sel:[1,0]
	v_mov_b32_e32 v9, v2
	v_pk_add_f32 v[6:7], v[10:11], v[6:7] neg_lo:[0,1] neg_hi:[0,1]
	v_mov_b32_e32 v14, v12
	v_pk_add_f32 v[2:3], v[8:9], v[6:7] neg_lo:[0,1] neg_hi:[0,1]
	v_mov_b32_e32 v13, v5
	v_pk_add_f32 v[6:7], v[14:15], v[2:3]
	v_cmp_neq_f32_e32 vcc, s6, v0
	v_pk_add_f32 v[8:9], v[6:7], v[6:7] op_sel:[0,1] op_sel_hi:[1,0]
	s_mov_b32 s6, 0x33800000
	v_pk_add_f32 v[4:5], v[4:5], v[8:9] op_sel:[1,0] op_sel_hi:[0,1]
	v_mov_b32_e32 v7, v4
	v_pk_add_f32 v[10:11], v[6:7], v[12:13] neg_lo:[0,1] neg_hi:[0,1]
	v_mov_b32_e32 v3, v8
	v_sub_f32_e32 v5, v6, v10
	v_pk_add_f32 v[2:3], v[2:3], v[10:11] neg_lo:[0,1] neg_hi:[0,1]
	v_sub_f32_e32 v5, v12, v5
	v_add_f32_e32 v2, v2, v5
	v_add_f32_e32 v2, v2, v3
	v_add_f32_e32 v2, v4, v2
	v_cndmask_b32_e32 v2, v183, v2, vcc
	v_cmp_lt_f32_e64 vcc, |v0|, s6
	s_nop 1
	v_cndmask_b32_e32 v0, v2, v0, vcc

.LBB0_1429:
	v_mov_b32_e32 v4, v252
	s_waitcnt vmcnt(63) expcnt(7) lgkmcnt(15)
	v_readfirstlane_b32 s4, v4
	s_ashr_i32 s10, s4, 6
	v_and_b32_e32 v173, 63, v4
	s_mul_i32 s5, s10, 0x410
	s_add_i32 s8, s5, 0
	s_add_i32 s11, s18, 0xffb9
	s_and_b32 s9, s11, 0xffff
	s_mul_i32 s2, s9, 0x8889
	s_lshr_b32 s2, s2, 22
	s_lshl_b32 s3, s2, 7
	s_mulk_i32 s2, 0x78
	s_sub_i32 s2, s11, s2
	s_add_i32 s2, s2, 8
	s_and_b32 s2, s2, 0xffff
	s_add_i32 s33, s3, s2
	s_lshr_b32 s2, s33, 7
	s_lshl_b32 s76, s2, 22
	s_lshl_b32 s2, s2, 3
	s_and_b32 s6, s4, 0xffffffc0
	s_add_i32 s2, s10, s2
	s_ashr_i32 s7, s6, 31
	s_ashr_i32 s3, s2, 31
	s_lshl_b64 s[2:3], s[2:3], 20
	s_lshl_b64 s[4:5], s[6:7], 1
	v_lshrrev_b32_e32 v5, 5, v173
	s_add_u32 s30, s95, s4
	v_and_b32_e32 v172, 31, v4
	s_addc_u32 s31, s22, s5
	v_lshlrev_b32_e32 v0, 4, v5
	v_lshl_add_u64 v[2:3], s[30:31], 0, v[0:1]
	v_lshl_or_b32 v0, s33, 6, v172
	v_lshlrev_b64 v[6:7], 10, v[0:1]
	v_or_b32_e32 v162, 32, v0
	v_mov_b32_e32 v163, v1
	v_lshl_add_u64 v[18:19], v[2:3], 0, v[6:7]
	v_lshlrev_b64 v[6:7], 10, v[162:163]
	s_waitcnt lgkmcnt(0)
	s_barrier
	v_lshl_add_u64 v[2:3], v[2:3], 0, v[6:7]
	global_load_dwordx4 v[6:9], v[18:19], off
	global_load_dwordx4 v[10:13], v[18:19], off offset:32
	global_load_dwordx4 v[14:17], v[18:19], off offset:64
	s_nop 0
	global_load_dwordx4 v[18:21], v[18:19], off offset:96
	s_nop 0
	global_load_dwordx4 v[22:25], v[2:3], off
	global_load_dwordx4 v[26:29], v[2:3], off offset:32
	global_load_dwordx4 v[30:33], v[2:3], off offset:64
	global_load_dwordx4 v[34:37], v[2:3], off offset:96
	s_mulk_i32 s10, 0x1bf0
	v_lshlrev_b32_e32 v38, 4, v173
	s_add_i32 s10, s8, s10
	v_and_b32_e32 v3, 32, v4
	v_add_u32_e32 v174, s10, v38
	s_lshl_b32 s10, s11, 16
	v_lshlrev_b32_e32 v2, 10, v172
	v_lshrrev_b32_e32 v3, 1, v3
	v_or3_b32 v2, s10, v2, v3
	s_lshl_b64 s[10:11], s[76:77], 1
	s_add_u32 s10, s10, s4
	v_mov_b32_e32 v3, v1
	s_addc_u32 s11, s11, s5
	v_lshl_add_u64 v[2:3], s[10:11], 0, v[2:3]
	s_mul_hi_u32 s10, s9, 0x2222223
	s_mul_hi_u32 s11, s10, 0x780000
	s_mul_i32 s30, s10, 0x780000
	v_subrev_co_u32_e32 v166, vcc, s30, v2
	v_mov_b32_e32 v2, s11
	s_lshl_b32 s9, s9, 13
	v_subb_co_u32_e32 v167, vcc, v3, v2, vcc
	s_add_u32 s2, s2, s9
	v_lshlrev_b32_e32 v2, 4, v172
	v_lshlrev_b32_e32 v3, 10, v5
	v_or3_b32 v2, v3, v2, s2
	s_addc_u32 s3, s3, 0
	v_or_b32_e32 v3, 0x200, v2
	s_mul_i32 s10, s10, 0xf0000
	v_mov_b32_e32 v4, s3
	v_subrev_co_u32_e32 v168, vcc, s10, v3
	v_lshlrev_b32_e32 v165, 2, v5
	s_nop 0
	v_subbrev_co_u32_e32 v169, vcc, 0, v4, vcc
	v_subrev_co_u32_e32 v170, vcc, s10, v2
	v_sub_u32_e32 v2, v172, v165
	s_nop 0
	v_subbrev_co_u32_e32 v171, vcc, 0, v4, vcc
	v_add_u32_e32 v177, 0x220, v2
	v_mov_b32_e32 v2, v1
	v_mov_b32_e32 v3, v1
	v_mov_b32_e32 v4, v1
	v_mov_b32_e32 v5, v1
	v_mov_b32_e32 v175, 0
	v_mov_b32_e32 v189, 0xf149f2ca
	s_mov_b32 s9, -1
	v_mov_b32_e32 v199, 0xf149f2ca
	v_mov_b32_e32 v176, 0
	v_readfirstlane_b32 s98, v252
	v_mbcnt_lo_u32_b32 v249, -1, 0
	v_mbcnt_hi_u32_b32 v249, -1, v249
	s_lshr_b32 s101, s98, 6
	s_lshl_b32 s98, s101, 13
	s_add_i32 s98, s98, 0x14000
	s_add_i32 s99, s98, 0x1c00
	s_mov_b32 s100, 0x1000
	s_cmp_eq_u32 s101, 7
	s_cselect_b32 s99, 0x3000, s99
	s_cselect_b32 s100, 0xfffe0400, s100
	v_and_b32_e32 v246, 31, v249
	v_lshrrev_b32_e32 v247, 5, v249
	v_bfe_u32 v248, v249, 1, 3
	v_lshl_add_u32 v250, v246, 7, s98
	v_xor_b32_e32 v241, v247, v248
	v_lshl_add_u32 v241, v241, 4, v250
	v_or_b32_e32 v242, 2, v247
	v_xor_b32_e32 v242, v242, v248
	v_lshl_add_u32 v242, v242, 4, v250
	v_or_b32_e32 v243, 4, v247
	v_xor_b32_e32 v243, v243, v248
	v_lshl_add_u32 v243, v243, 4, v250
	v_or_b32_e32 v244, 6, v247
	v_xor_b32_e32 v244, v244, v248
	v_lshl_add_u32 v244, v244, 4, v250
	v_mov_b32_e32 v245, 0x1000
	v_mov_b32_e32 v251, s100
	v_cmp_lt_u32_e32 vcc, 23, v246
	s_nop 1
	v_cndmask_b32_e32 v245, v245, v251, vcc
	v_add_u32_e32 v248, v244, v245
	v_add_u32_e32 v247, v243, v245
	v_add_u32_e32 v246, v242, v245
	v_add_u32_e32 v245, v241, v245
	v_lshrrev_b32_e32 v250, 3, v249
	v_lshlrev_b32_e32 v250, 10, v250
	v_and_b32_e32 v251, 7, v249
	v_lshrrev_b32_e32 v142, 4, v249
	v_xor_b32_e32 v251, v251, v142
	v_lshl_add_u32 v142, v251, 4, v250
	v_xor_b32_e32 v251, 4, v251
	v_lshl_add_u32 v250, v251, 4, v250
	v_add_u32_e32 v250, 0x2000, v250
	v_readfirstlane_b32 s100, v166
	v_readfirstlane_b32 s101, v167
	s_nop 0
	s_add_u32 s100, s100, s86
	s_addc_u32 s101, s101, s87
	s_add_u32 s100, s100, 0x85ee200
	s_addc_u32 s101, s101, 0
	v_mov_b32_e32 v143, 0
	v_mov_b32_e32 v251, 0
	v_lshl_add_u64 v[166:167], s[100:101], 0, v[142:143]
	v_lshl_add_u64 v[250:251], s[100:101], 0, v[250:251]
	s_mov_b64 s[100:101], 0x4000
	s_mov_b32 m0, s98
	s_nop 0
	global_load_lds_dwordx4 v[166:167], off
	s_add_i32 m0, s98, 0x400
	s_nop 0
	global_load_lds_dwordx4 v[250:251], off
	v_lshl_add_u64 v[142:143], v[166:167], 0, s[100:101]
	s_add_i32 m0, s98, 0x800
	s_nop 0
	global_load_lds_dwordx4 v[142:143], off
	v_lshl_add_u64 v[144:145], v[250:251], 0, s[100:101]
	s_add_i32 m0, s98, 0xc00
	s_nop 0
	global_load_lds_dwordx4 v[144:145], off
	v_lshl_add_u64 v[142:143], v[142:143], 0, s[100:101]
	s_add_i32 m0, s98, 0x1000
	s_nop 0
	global_load_lds_dwordx4 v[142:143], off
	v_lshl_add_u64 v[144:145], v[144:145], 0, s[100:101]
	s_add_i32 m0, s98, 0x1400
	s_nop 0
	global_load_lds_dwordx4 v[144:145], off
	v_lshl_add_u64 v[142:143], v[142:143], 0, s[100:101]
	s_add_i32 m0, s98, 0x1800
	s_nop 0
	global_load_lds_dwordx4 v[142:143], off
	v_lshl_add_u64 v[144:145], v[144:145], 0, s[100:101]
	s_mov_b32 m0, s99
	s_nop 0
	global_load_lds_dwordx4 v[144:145], off
	s_load_dwordx2 s[2:3], s[0:1], 0x40
	s_sub_i32 s10, s98, 0x14000
	s_lshr_b32 s10, s10, 13
	s_mul_i32 s10, s10, 0x101
	v_add_u32_e32 v44, s10, v173
	v_ashrrev_i32_e32 v45, 31, v44
	v_lshl_add_u32 v43, v173, 2, s8
	s_waitcnt lgkmcnt(0)
	v_lshl_add_u64 v[44:45], v[44:45], 2, s[2:3]
	global_load_dword v38, v[44:45], off
	global_load_dword v39, v[44:45], off offset:256
	global_load_dword v40, v[44:45], off offset:512
	global_load_dword v41, v[44:45], off offset:768
	v_cmp_eq_u32_e32 vcc, 0, v173
	s_and_saveexec_b64 s[2:3], vcc
	global_load_dword v42, v[44:45], off offset:1024
	s_waitcnt vmcnt(0)
	v_mul_f32_e32 v42, 0x3fb8aa3b, v42
	ds_write_b32 v43, v42 offset:1024
	ds_write_b32 v43, v42 offset:1028
	ds_write_b32 v43, v42 offset:1032
	ds_write_b32 v43, v42 offset:1036
	s_or_b64 exec, exec, s[2:3]
	v_mul_f32_e32 v38, 0x3fb8aa3b, v38
	v_mul_f32_e32 v39, 0x3fb8aa3b, v39
	v_mul_f32_e32 v40, 0x3fb8aa3b, v40
	v_mul_f32_e32 v41, 0x3fb8aa3b, v41
	ds_write_b32 v43, v38
	ds_write_b32 v43, v39 offset:256
	ds_write_b32 v43, v40 offset:512
	ds_write_b32 v43, v41 offset:768
	s_waitcnt vmcnt(7)
	s_waitcnt vmcnt(6)
	s_waitcnt vmcnt(5)
	s_waitcnt vmcnt(4)
	s_waitcnt vmcnt(3)
	s_waitcnt vmcnt(2)
	s_waitcnt vmcnt(1)
	s_waitcnt vmcnt(0)
	ds_write_b128 v174, v[6:9] offset:16384
	ds_write_b128 v174, v[10:13] offset:17408
	ds_write_b128 v174, v[14:17] offset:18432
	ds_write_b128 v174, v[18:21] offset:19456
	ds_write_b128 v174, v[22:25] offset:20480
	ds_write_b128 v174, v[26:29] offset:21504
	ds_write_b128 v174, v[30:33] offset:22528
	ds_write_b128 v174, v[34:37] offset:23552
	v_mov_b32_e32 v16, v1
	v_mov_b32_e32 v17, v1
	v_mov_b32_e32 v6, v1
	v_mov_b32_e32 v7, v1
	v_mov_b32_e32 v8, v1
	v_mov_b32_e32 v9, v1
	v_mov_b32_e32 v10, v1
	v_mov_b32_e32 v11, v1
	v_mov_b32_e32 v12, v1
	v_mov_b32_e32 v13, v1
	v_mov_b32_e32 v14, v1
	v_mov_b32_e32 v15, v1
	v_mov_b64_e32 v[48:49], v[16:17]
	v_mov_b64_e32 v[32:33], v[16:17]
	v_mov_b64_e32 v[64:65], v[16:17]
	v_mov_b64_e32 v[46:47], v[14:15]
	v_mov_b64_e32 v[44:45], v[12:13]
	v_mov_b64_e32 v[42:43], v[10:11]
	v_mov_b64_e32 v[40:41], v[8:9]
	v_mov_b64_e32 v[38:39], v[6:7]
	v_mov_b64_e32 v[36:37], v[4:5]
	v_mov_b64_e32 v[34:35], v[2:3]
	v_mov_b64_e32 v[30:31], v[14:15]
	v_mov_b64_e32 v[28:29], v[12:13]
	v_mov_b64_e32 v[26:27], v[10:11]
	v_mov_b64_e32 v[24:25], v[8:9]
	v_mov_b64_e32 v[22:23], v[6:7]
	v_mov_b64_e32 v[20:21], v[4:5]
	v_mov_b64_e32 v[18:19], v[2:3]
	v_mov_b64_e32 v[62:63], v[14:15]
	v_mov_b64_e32 v[60:61], v[12:13]
	v_mov_b64_e32 v[58:59], v[10:11]
	v_mov_b64_e32 v[56:57], v[8:9]
	v_mov_b64_e32 v[54:55], v[6:7]
	v_mov_b64_e32 v[52:53], v[4:5]
	v_mov_b64_e32 v[50:51], v[2:3]
	v_mov_b32_e32 v216, 0x3e38aa3b
	v_mov_b32_e32 v217, 0x3e38aa3b
	v_xor_b32_e32 v249, 32, v179
	v_lshlrev_b32_e32 v249, 2, v249

.Lattn_nopf:
	v_lshl_add_u64 v[130:131], s[86:87], 0, v[170:171]
	v_add_co_u32_e32 v132, vcc, s88, v130
	s_nop 1
	v_addc_co_u32_e32 v133, vcc, 0, v131, vcc
	v_add_co_u32_e32 v130, vcc, s17, v130
	global_load_dwordx4 v[158:161], v[132:133], off offset:512
	global_load_dwordx4 v[154:157], v[132:133], off offset:1024
	global_load_dwordx4 v[150:153], v[132:133], off offset:2560
	global_load_dwordx4 v[146:149], v[132:133], off offset:3072
	v_addc_co_u32_e32 v131, vcc, 0, v131, vcc
	v_lshl_add_u64 v[132:133], s[86:87], 0, v[168:169]
	v_add_co_u32_e32 v132, vcc, 0xae6f000, v132
	s_nop 1
	v_addc_co_u32_e32 v133, vcc, 0, v133, vcc
	global_load_dwordx4 v[138:141], v[130:131], off offset:512
	global_load_dwordx4 v[134:137], v[130:131], off offset:2560
	global_load_dwordx4 v[142:145], v[132:133], off offset:512
	s_nop 0
	global_load_dwordx4 v[130:133], v[132:133], off offset:2560
	v_mov_b32_e32 v188, s8
	ds_read_b32 v190, v188 offset:1024
	s_cmp_lt_u32 s9, 6
	s_cbranch_scc0 .Lattn_far_p
	s_waitcnt vmcnt(8)
	v_subrev_u32_e32 v177, 64, v177
	v_max3_f32 v231, v98, v99, v100
	v_max3_f32 v231, v231, v101, v102
	v_max3_f32 v231, v231, v103, v104
	v_max3_f32 v231, v231, v105, v106
	v_max3_f32 v231, v231, v107, v108
	v_max3_f32 v231, v231, v109, v110
	v_max3_f32 v231, v231, v111, v112
	v_max3_f32 v231, v231, v113, v114
	v_max3_f32 v231, v231, v115, v116
	v_max3_f32 v231, v231, v117, v118
	v_max3_f32 v231, v231, v119, v120
	v_max3_f32 v231, v231, v121, v122
	v_max3_f32 v231, v231, v123, v124
	v_max3_f32 v231, v231, v125, v126
	v_max3_f32 v231, v231, v127, v128
	v_max_f32_e32 v231, v231, v129
	s_waitcnt lgkmcnt(0)
	v_fma_f32 v231, v231, v216, v190
	ds_bpermute_b32 v233, v249, v231
	v_max3_f32 v234, v66, v67, v68
	v_max3_f32 v234, v234, v69, v70
	v_max3_f32 v234, v234, v71, v72
	v_max3_f32 v234, v234, v73, v74
	v_max3_f32 v234, v234, v75, v76
	v_max3_f32 v234, v234, v77, v78
	v_max3_f32 v234, v234, v79, v80
	v_max3_f32 v234, v234, v81, v82
	v_max3_f32 v234, v234, v83, v84
	v_max3_f32 v234, v234, v85, v86
	v_max3_f32 v234, v234, v87, v88
	v_max3_f32 v234, v234, v89, v90
	v_max3_f32 v234, v234, v91, v92
	v_max3_f32 v234, v234, v93, v94
	v_max3_f32 v234, v234, v95, v96
	v_max_f32_e32 v234, v234, v97
	v_fma_f32 v234, v234, v216, v190
	ds_bpermute_b32 v235, v249, v234
	s_waitcnt lgkmcnt(1)
	v_max3_f32 v236, v199, v231, v233
	v_sub_f32_e32 v226, v199, v236
	v_sub_f32_e32 v238, v190, v236
	v_sub_f32_e32 v239, v190, v236
	v_exp_f32_e32 v226, v226
	v_pk_fma_f32 v[98:99], v[98:99], v[216:217], v[238:239]
	v_pk_fma_f32 v[100:101], v[100:101], v[216:217], v[238:239]
	v_pk_fma_f32 v[102:103], v[102:103], v[216:217], v[238:239]
	v_pk_fma_f32 v[104:105], v[104:105], v[216:217], v[238:239]
	v_pk_fma_f32 v[106:107], v[106:107], v[216:217], v[238:239]
	v_pk_fma_f32 v[108:109], v[108:109], v[216:217], v[238:239]
	v_pk_fma_f32 v[110:111], v[110:111], v[216:217], v[238:239]
	v_pk_fma_f32 v[112:113], v[112:113], v[216:217], v[238:239]
	v_pk_fma_f32 v[114:115], v[114:115], v[216:217], v[238:239]
	v_pk_fma_f32 v[116:117], v[116:117], v[216:217], v[238:239]
	v_pk_fma_f32 v[118:119], v[118:119], v[216:217], v[238:239]
	v_pk_fma_f32 v[120:121], v[120:121], v[216:217], v[238:239]
	v_pk_fma_f32 v[122:123], v[122:123], v[216:217], v[238:239]
	v_pk_fma_f32 v[124:125], v[124:125], v[216:217], v[238:239]
	v_pk_fma_f32 v[126:127], v[126:127], v[216:217], v[238:239]
	v_pk_fma_f32 v[128:129], v[128:129], v[216:217], v[238:239]
	v_exp_f32_e32 v98, v98
	v_exp_f32_e32 v99, v99
	v_exp_f32_e32 v100, v100
	v_exp_f32_e32 v101, v101
	v_exp_f32_e32 v102, v102
	v_exp_f32_e32 v103, v103
	v_exp_f32_e32 v104, v104
	v_exp_f32_e32 v105, v105
	v_exp_f32_e32 v106, v106
	v_exp_f32_e32 v107, v107
	v_exp_f32_e32 v108, v108
	v_exp_f32_e32 v109, v109
	v_exp_f32_e32 v110, v110
	v_exp_f32_e32 v111, v111
	v_exp_f32_e32 v112, v112
	v_exp_f32_e32 v113, v113
	v_exp_f32_e32 v114, v114
	v_exp_f32_e32 v115, v115
	v_exp_f32_e32 v116, v116
	v_exp_f32_e32 v117, v117
	v_exp_f32_e32 v118, v118
	v_exp_f32_e32 v119, v119
	v_exp_f32_e32 v120, v120
	v_exp_f32_e32 v121, v121
	v_exp_f32_e32 v122, v122
	v_exp_f32_e32 v123, v123
	v_exp_f32_e32 v124, v124
	v_exp_f32_e32 v125, v125
	v_exp_f32_e32 v126, v126
	v_exp_f32_e32 v127, v127
	v_exp_f32_e32 v128, v128
	v_exp_f32_e32 v129, v129
	s_waitcnt lgkmcnt(0)
	v_max3_f32 v218, v189, v234, v235
	v_sub_f32_e32 v228, v189, v218
	v_sub_f32_e32 v202, v190, v218
	v_sub_f32_e32 v203, v190, v218
	v_exp_f32_e32 v228, v228
	v_pk_fma_f32 v[66:67], v[66:67], v[216:217], v[202:203]
	v_pk_fma_f32 v[68:69], v[68:69], v[216:217], v[202:203]
	v_pk_fma_f32 v[70:71], v[70:71], v[216:217], v[202:203]
	v_pk_fma_f32 v[72:73], v[72:73], v[216:217], v[202:203]
	v_pk_fma_f32 v[74:75], v[74:75], v[216:217], v[202:203]
	v_pk_fma_f32 v[76:77], v[76:77], v[216:217], v[202:203]
	v_pk_fma_f32 v[78:79], v[78:79], v[216:217], v[202:203]
	v_pk_fma_f32 v[80:81], v[80:81], v[216:217], v[202:203]
	v_pk_fma_f32 v[82:83], v[82:83], v[216:217], v[202:203]
	v_pk_fma_f32 v[84:85], v[84:85], v[216:217], v[202:203]
	v_pk_fma_f32 v[86:87], v[86:87], v[216:217], v[202:203]
	v_pk_fma_f32 v[88:89], v[88:89], v[216:217], v[202:203]
	v_pk_fma_f32 v[90:91], v[90:91], v[216:217], v[202:203]
	v_pk_fma_f32 v[92:93], v[92:93], v[216:217], v[202:203]
	v_pk_fma_f32 v[94:95], v[94:95], v[216:217], v[202:203]
	v_pk_fma_f32 v[96:97], v[96:97], v[216:217], v[202:203]
	v_exp_f32_e32 v66, v66
	v_exp_f32_e32 v67, v67
	v_exp_f32_e32 v68, v68
	v_exp_f32_e32 v69, v69
	v_exp_f32_e32 v70, v70
	v_exp_f32_e32 v71, v71
	v_exp_f32_e32 v72, v72
	v_exp_f32_e32 v73, v73
	v_exp_f32_e32 v74, v74
	v_exp_f32_e32 v75, v75
	v_exp_f32_e32 v76, v76
	v_exp_f32_e32 v77, v77
	v_exp_f32_e32 v78, v78
	v_exp_f32_e32 v79, v79
	v_exp_f32_e32 v80, v80
	v_exp_f32_e32 v81, v81
	v_exp_f32_e32 v82, v82
	v_exp_f32_e32 v83, v83
	v_exp_f32_e32 v84, v84
	v_exp_f32_e32 v85, v85
	v_exp_f32_e32 v86, v86
	v_exp_f32_e32 v87, v87
	v_exp_f32_e32 v88, v88
	v_exp_f32_e32 v89, v89
	v_exp_f32_e32 v90, v90
	v_exp_f32_e32 v91, v91
	v_exp_f32_e32 v92, v92
	v_exp_f32_e32 v93, v93
	v_exp_f32_e32 v94, v94
	v_exp_f32_e32 v95, v95
	v_exp_f32_e32 v96, v96
	v_exp_f32_e32 v97, v97
	v_pk_add_f32 v[212:213], v[98:99], v[100:101]
	v_pk_add_f32 v[214:215], v[102:103], v[104:105]
	v_pk_add_f32 v[212:213], v[212:213], v[106:107]
	v_pk_add_f32 v[214:215], v[214:215], v[108:109]
	v_pk_add_f32 v[212:213], v[212:213], v[110:111]
	v_pk_add_f32 v[214:215], v[214:215], v[112:113]
	v_pk_add_f32 v[212:213], v[212:213], v[114:115]
	v_pk_add_f32 v[214:215], v[214:215], v[116:117]
	v_pk_add_f32 v[212:213], v[212:213], v[118:119]
	v_pk_add_f32 v[214:215], v[214:215], v[120:121]
	v_pk_add_f32 v[212:213], v[212:213], v[122:123]
	v_pk_add_f32 v[214:215], v[214:215], v[124:125]
	v_pk_add_f32 v[212:213], v[212:213], v[126:127]
	v_pk_add_f32 v[214:215], v[214:215], v[128:129]
	v_pk_add_f32 v[212:213], v[212:213], v[214:215]
	v_add_f32_e32 v210, v212, v213
	ds_bpermute_b32 v211, v249, v210
	v_pk_add_f32 v[220:221], v[66:67], v[68:69]
	v_pk_add_f32 v[222:223], v[70:71], v[72:73]
	v_pk_add_f32 v[220:221], v[220:221], v[74:75]
	v_pk_add_f32 v[222:223], v[222:223], v[76:77]
	v_pk_add_f32 v[220:221], v[220:221], v[78:79]
	v_pk_add_f32 v[222:223], v[222:223], v[80:81]
	v_pk_add_f32 v[220:221], v[220:221], v[82:83]
	v_pk_add_f32 v[222:223], v[222:223], v[84:85]
	v_pk_add_f32 v[220:221], v[220:221], v[86:87]
	v_pk_add_f32 v[222:223], v[222:223], v[88:89]
	v_pk_add_f32 v[220:221], v[220:221], v[90:91]
	v_pk_add_f32 v[222:223], v[222:223], v[92:93]
	v_pk_add_f32 v[220:221], v[220:221], v[94:95]
	v_pk_add_f32 v[222:223], v[222:223], v[96:97]
	v_pk_add_f32 v[220:221], v[220:221], v[222:223]
	v_add_f32_e32 v224, v220, v221
	ds_bpermute_b32 v225, v249, v224
	v_cmp_neq_f32_e32 vcc, 1.0, v226
	s_cbranch_vccz .Lattn_near_p_sa
	v_mov_b32_e32 v227, v226
	v_pk_mul_f32 v[64:65], v[64:65], v[226:227]
	v_pk_mul_f32 v[62:63], v[62:63], v[226:227]
	v_pk_mul_f32 v[60:61], v[60:61], v[226:227]
	v_pk_mul_f32 v[58:59], v[58:59], v[226:227]
	v_pk_mul_f32 v[56:57], v[56:57], v[226:227]
	v_pk_mul_f32 v[54:55], v[54:55], v[226:227]
	v_pk_mul_f32 v[52:53], v[52:53], v[226:227]
	v_pk_mul_f32 v[50:51], v[50:51], v[226:227]
	v_pk_mul_f32 v[48:49], v[48:49], v[226:227]
	v_pk_mul_f32 v[46:47], v[46:47], v[226:227]
	v_pk_mul_f32 v[44:45], v[44:45], v[226:227]
	v_pk_mul_f32 v[42:43], v[42:43], v[226:227]
	v_pk_mul_f32 v[40:41], v[40:41], v[226:227]
	v_pk_mul_f32 v[38:39], v[38:39], v[226:227]
	v_pk_mul_f32 v[36:37], v[36:37], v[226:227]
	v_pk_mul_f32 v[34:35], v[34:35], v[226:227]

.Lattn_near_p_sb:
	v_cvt_pk_bf16_f32 v98, v98, v99
	v_cvt_pk_bf16_f32 v99, v100, v101
	v_cvt_pk_bf16_f32 v100, v102, v103
	v_cvt_pk_bf16_f32 v101, v104, v105
	v_cvt_pk_bf16_f32 v66, v66, v67
	v_cvt_pk_bf16_f32 v67, v68, v69
	v_cvt_pk_bf16_f32 v68, v70, v71
	v_cvt_pk_bf16_f32 v69, v72, v73
	s_waitcnt vmcnt(7)
	v_mfma_f32_32x32x16_bf16 v[50:65], v[158:161], v[98:101], v[50:65]
	v_cvt_pk_bf16_f32 v102, v106, v107
	v_cvt_pk_bf16_f32 v103, v108, v109
	v_cvt_pk_bf16_f32 v104, v110, v111
	v_cvt_pk_bf16_f32 v105, v112, v113
	v_mfma_f32_32x32x16_bf16 v[18:33], v[158:161], v[66:69], v[18:33]
	v_cvt_pk_bf16_f32 v70, v74, v75
	v_cvt_pk_bf16_f32 v71, v76, v77
	v_cvt_pk_bf16_f32 v72, v78, v79
	v_cvt_pk_bf16_f32 v73, v80, v81
	s_waitcnt vmcnt(6)
	v_mfma_f32_32x32x16_bf16 v[34:49], v[154:157], v[98:101], v[34:49]
	v_mfma_f32_32x32x16_bf16 v[2:17], v[154:157], v[66:69], v[2:17]
	v_cvt_pk_bf16_f32 v106, v114, v115
	v_cvt_pk_bf16_f32 v107, v116, v117
	v_cvt_pk_bf16_f32 v108, v118, v119
	v_cvt_pk_bf16_f32 v109, v120, v121
	v_cvt_pk_bf16_f32 v74, v82, v83
	v_cvt_pk_bf16_f32 v75, v84, v85
	v_cvt_pk_bf16_f32 v76, v86, v87
	v_cvt_pk_bf16_f32 v77, v88, v89
	s_waitcnt vmcnt(5)
	v_mfma_f32_32x32x16_bf16 v[50:65], v[150:153], v[102:105], v[50:65]
	v_mfma_f32_32x32x16_bf16 v[18:33], v[150:153], v[70:73], v[18:33]
	s_waitcnt vmcnt(4)
	v_mfma_f32_32x32x16_bf16 v[34:49], v[146:149], v[102:105], v[34:49]
	v_mfma_f32_32x32x16_bf16 v[2:17], v[146:149], v[70:73], v[2:17]
	v_cvt_pk_bf16_f32 v110, v122, v123
	v_cvt_pk_bf16_f32 v111, v124, v125
	v_cvt_pk_bf16_f32 v112, v126, v127
	v_cvt_pk_bf16_f32 v113, v128, v129
	v_cvt_pk_bf16_f32 v78, v90, v91
	v_cvt_pk_bf16_f32 v79, v92, v93
	v_cvt_pk_bf16_f32 v80, v94, v95
	v_cvt_pk_bf16_f32 v81, v96, v97
	s_waitcnt vmcnt(3)
	v_mfma_f32_32x32x16_bf16 v[50:65], v[138:141], v[106:109], v[50:65]
	v_mfma_f32_32x32x16_bf16 v[18:33], v[138:141], v[74:77], v[18:33]
	s_waitcnt vmcnt(1)
	v_mfma_f32_32x32x16_bf16 v[34:49], v[142:145], v[106:109], v[34:49]
	v_mfma_f32_32x32x16_bf16 v[2:17], v[142:145], v[74:77], v[2:17]
	v_mfma_f32_32x32x16_bf16 v[50:65], v[134:137], v[110:113], v[50:65]
	v_mfma_f32_32x32x16_bf16 v[18:33], v[134:137], v[78:81], v[18:33]
	s_waitcnt lgkmcnt(0)
	v_add_f32_e32 v210, v210, v211
	v_add_f32_e32 v224, v224, v225
	v_fma_f32 v176, v176, v226, v210
	v_fma_f32 v175, v175, v228, v224
	v_lshl_add_u64 v[168:169], v[168:169], 0, s[84:85]
	v_lshl_add_u64 v[170:171], v[170:171], 0, s[84:85]
	s_waitcnt vmcnt(0)
	v_mfma_f32_32x32x16_bf16 v[34:49], v[130:133], v[110:113], v[34:49]
	v_mfma_f32_32x32x16_bf16 v[2:17], v[130:133], v[78:81], v[2:17]
	v_mov_b32_e32 v189, v218
	v_mov_b32_e32 v199, v236
	s_branch .LBB0_1432
.Lattn_far_p:
	s_waitcnt vmcnt(8)
	v_lshl_add_u32 v191, v177, 2, s8
	v_subrev_u32_e32 v177, 64, v177
	s_add_i32 s2, s8, 0x200
	v_add_u32_e32 v192, 0xfffffff4, v191
	v_min_i32_e32 v192, s2, v192
	ds_read2_b32 v[200:201], v192 offset0:131 offset1:130
	ds_read2_b32 v[202:203], v192 offset0:129 offset1:128
	v_add_u32_e32 v193, 0xffffffd4, v191
	v_min_i32_e32 v193, s2, v193
	ds_read2_b32 v[204:205], v193 offset0:131 offset1:130
	ds_read2_b32 v[206:207], v193 offset0:129 offset1:128
	v_add_u32_e32 v192, 0xffffffb4, v191
	v_min_i32_e32 v192, s2, v192
	ds_read2_b32 v[208:209], v192 offset0:131 offset1:130
	ds_read2_b32 v[210:211], v192 offset0:129 offset1:128
	v_add_u32_e32 v193, 0xffffff94, v191
	v_min_i32_e32 v193, s2, v193
	ds_read2_b32 v[212:213], v193 offset0:131 offset1:130
	ds_read2_b32 v[214:215], v193 offset0:129 offset1:128
	v_add_u32_e32 v192, 0xffffff74, v191
	v_min_i32_e32 v192, s2, v192
	ds_read2_b32 v[218:219], v192 offset0:131 offset1:130
	ds_read2_b32 v[220:221], v192 offset0:129 offset1:128
	v_add_u32_e32 v193, 0xffffff54, v191
	v_min_i32_e32 v193, s2, v193
	ds_read2_b32 v[222:223], v193 offset0:131 offset1:130
	ds_read2_b32 v[224:225], v193 offset0:129 offset1:128
	v_add_u32_e32 v192, 0xffffff34, v191
	v_min_i32_e32 v192, s2, v192
	ds_read2_b32 v[226:227], v192 offset0:131 offset1:130
	ds_read2_b32 v[228:229], v192 offset0:129 offset1:128
	s_waitcnt lgkmcnt(6)
	v_pk_fma_f32 v[66:67], v[66:67], v[216:217], v[200:201]
	v_pk_fma_f32 v[68:69], v[68:69], v[216:217], v[202:203]
	v_pk_fma_f32 v[70:71], v[70:71], v[216:217], v[204:205]
	v_pk_fma_f32 v[72:73], v[72:73], v[216:217], v[206:207]
	v_pk_fma_f32 v[74:75], v[74:75], v[216:217], v[208:209]
	v_pk_fma_f32 v[76:77], v[76:77], v[216:217], v[210:211]
	v_pk_fma_f32 v[78:79], v[78:79], v[216:217], v[212:213]
	v_pk_fma_f32 v[80:81], v[80:81], v[216:217], v[214:215]
	v_add_u32_e32 v193, 0xffffff14, v191
	v_min_i32_e32 v193, s2, v193
	ds_read2_b32 v[230:231], v193 offset0:131 offset1:130
	ds_read2_b32 v[232:233], v193 offset0:129 offset1:128
	v_add_u32_e32 v192, 0xfffffef4, v191
	v_min_i32_e32 v192, s2, v192
	ds_read2_b32 v[200:201], v192 offset0:131 offset1:130
	ds_read2_b32 v[202:203], v192 offset0:129 offset1:128
	v_add_u32_e32 v193, 0xfffffed4, v191
	v_min_i32_e32 v193, s2, v193
	ds_read2_b32 v[204:205], v193 offset0:131 offset1:130
	ds_read2_b32 v[206:207], v193 offset0:129 offset1:128
	v_add_u32_e32 v192, 0xfffffeb4, v191
	v_min_i32_e32 v192, s2, v192
	ds_read2_b32 v[208:209], v192 offset0:131 offset1:130
	ds_read2_b32 v[210:211], v192 offset0:129 offset1:128
	s_waitcnt lgkmcnt(6)
	v_pk_fma_f32 v[98:99], v[98:99], v[216:217], v[218:219]
	v_pk_fma_f32 v[100:101], v[100:101], v[216:217], v[220:221]
	v_pk_fma_f32 v[102:103], v[102:103], v[216:217], v[222:223]
	v_pk_fma_f32 v[104:105], v[104:105], v[216:217], v[224:225]
	v_pk_fma_f32 v[106:107], v[106:107], v[216:217], v[226:227]
	v_pk_fma_f32 v[108:109], v[108:109], v[216:217], v[228:229]
	v_pk_fma_f32 v[110:111], v[110:111], v[216:217], v[230:231]
	v_pk_fma_f32 v[112:113], v[112:113], v[216:217], v[232:233]
	v_pk_fma_f32 v[82:83], v[82:83], v[216:217], v[218:219]
	v_pk_fma_f32 v[84:85], v[84:85], v[216:217], v[220:221]
	v_pk_fma_f32 v[86:87], v[86:87], v[216:217], v[222:223]
	v_pk_fma_f32 v[88:89], v[88:89], v[216:217], v[224:225]
	v_pk_fma_f32 v[90:91], v[90:91], v[216:217], v[226:227]
	v_pk_fma_f32 v[92:93], v[92:93], v[216:217], v[228:229]
	v_pk_fma_f32 v[94:95], v[94:95], v[216:217], v[230:231]
	v_pk_fma_f32 v[96:97], v[96:97], v[216:217], v[232:233]
	v_add_u32_e32 v193, 0xfffffe94, v191
	v_min_i32_e32 v193, s2, v193
	ds_read2_b32 v[212:213], v193 offset0:131 offset1:130
	ds_read2_b32 v[214:215], v193 offset0:129 offset1:128
	s_waitcnt lgkmcnt(0)
	v_pk_fma_f32 v[114:115], v[114:115], v[216:217], v[200:201]
	v_pk_fma_f32 v[116:117], v[116:117], v[216:217], v[202:203]
	v_pk_fma_f32 v[118:119], v[118:119], v[216:217], v[204:205]
	v_pk_fma_f32 v[120:121], v[120:121], v[216:217], v[206:207]
	v_pk_fma_f32 v[122:123], v[122:123], v[216:217], v[208:209]
	v_pk_fma_f32 v[124:125], v[124:125], v[216:217], v[210:211]
	v_pk_fma_f32 v[126:127], v[126:127], v[216:217], v[212:213]
	v_pk_fma_f32 v[128:129], v[128:129], v[216:217], v[214:215]
	v_max3_f32 v231, v98, v99, v100
	v_max3_f32 v231, v231, v101, v102
	v_max3_f32 v231, v231, v103, v104
	v_max3_f32 v231, v231, v105, v106
	v_max3_f32 v231, v231, v107, v108
	v_max3_f32 v231, v231, v109, v110
	v_max3_f32 v231, v231, v111, v112
	v_max3_f32 v231, v231, v113, v114
	v_max3_f32 v231, v231, v115, v116
	v_max3_f32 v231, v231, v117, v118
	v_max3_f32 v231, v231, v119, v120
	v_max3_f32 v231, v231, v121, v122
	v_max3_f32 v231, v231, v123, v124
	v_max3_f32 v231, v231, v125, v126
	v_max3_f32 v231, v231, v127, v128
	v_max_f32_e32 v231, v231, v129
	ds_bpermute_b32 v233, v249, v231
	v_max3_f32 v234, v66, v67, v68
	v_max3_f32 v234, v234, v69, v70
	v_max3_f32 v234, v234, v71, v72
	v_max3_f32 v234, v234, v73, v74
	v_max3_f32 v234, v234, v75, v76
	v_max3_f32 v234, v234, v77, v78
	v_max3_f32 v234, v234, v79, v80
	v_max3_f32 v234, v234, v81, v82
	v_max3_f32 v234, v234, v83, v84
	v_max3_f32 v234, v234, v85, v86
	v_max3_f32 v234, v234, v87, v88
	v_max3_f32 v234, v234, v89, v90
	v_max3_f32 v234, v234, v91, v92
	v_max3_f32 v234, v234, v93, v94
	v_max3_f32 v234, v234, v95, v96
	v_max_f32_e32 v234, v234, v97
	ds_bpermute_b32 v235, v249, v234
	s_waitcnt lgkmcnt(1)
	v_max3_f32 v236, v199, v231, v233
	v_sub_f32_e32 v226, v199, v236
	v_sub_f32_e32 v238, 0, v236
	v_sub_f32_e32 v239, 0, v236
	v_exp_f32_e32 v226, v226
	v_pk_add_f32 v[98:99], v[98:99], v[238:239]
	v_pk_add_f32 v[100:101], v[100:101], v[238:239]
	v_pk_add_f32 v[102:103], v[102:103], v[238:239]
	v_pk_add_f32 v[104:105], v[104:105], v[238:239]
	v_pk_add_f32 v[106:107], v[106:107], v[238:239]
	v_pk_add_f32 v[108:109], v[108:109], v[238:239]
	v_pk_add_f32 v[110:111], v[110:111], v[238:239]
	v_pk_add_f32 v[112:113], v[112:113], v[238:239]
	v_pk_add_f32 v[114:115], v[114:115], v[238:239]
	v_pk_add_f32 v[116:117], v[116:117], v[238:239]
	v_pk_add_f32 v[118:119], v[118:119], v[238:239]
	v_pk_add_f32 v[120:121], v[120:121], v[238:239]
	v_pk_add_f32 v[122:123], v[122:123], v[238:239]
	v_pk_add_f32 v[124:125], v[124:125], v[238:239]
	v_pk_add_f32 v[126:127], v[126:127], v[238:239]
	v_pk_add_f32 v[128:129], v[128:129], v[238:239]
	v_exp_f32_e32 v98, v98
	v_exp_f32_e32 v99, v99
	v_exp_f32_e32 v100, v100
	v_exp_f32_e32 v101, v101
	v_exp_f32_e32 v102, v102
	v_exp_f32_e32 v103, v103
	v_exp_f32_e32 v104, v104
	v_exp_f32_e32 v105, v105
	v_exp_f32_e32 v106, v106
	v_exp_f32_e32 v107, v107
	v_exp_f32_e32 v108, v108
	v_exp_f32_e32 v109, v109
	v_exp_f32_e32 v110, v110
	v_exp_f32_e32 v111, v111
	v_exp_f32_e32 v112, v112
	v_exp_f32_e32 v113, v113
	v_exp_f32_e32 v114, v114
	v_exp_f32_e32 v115, v115
	v_exp_f32_e32 v116, v116
	v_exp_f32_e32 v117, v117
	v_exp_f32_e32 v118, v118
	v_exp_f32_e32 v119, v119
	v_exp_f32_e32 v120, v120
	v_exp_f32_e32 v121, v121
	v_exp_f32_e32 v122, v122
	v_exp_f32_e32 v123, v123
	v_exp_f32_e32 v124, v124
	v_exp_f32_e32 v125, v125
	v_exp_f32_e32 v126, v126
	v_exp_f32_e32 v127, v127
	v_exp_f32_e32 v128, v128
	v_exp_f32_e32 v129, v129
	s_waitcnt lgkmcnt(0)
	v_max3_f32 v218, v189, v234, v235
	v_sub_f32_e32 v228, v189, v218
	v_sub_f32_e32 v202, 0, v218
	v_sub_f32_e32 v203, 0, v218
	v_exp_f32_e32 v228, v228
	v_pk_add_f32 v[66:67], v[66:67], v[202:203]
	v_pk_add_f32 v[68:69], v[68:69], v[202:203]
	v_pk_add_f32 v[70:71], v[70:71], v[202:203]
	v_pk_add_f32 v[72:73], v[72:73], v[202:203]
	v_pk_add_f32 v[74:75], v[74:75], v[202:203]
	v_pk_add_f32 v[76:77], v[76:77], v[202:203]
	v_pk_add_f32 v[78:79], v[78:79], v[202:203]
	v_pk_add_f32 v[80:81], v[80:81], v[202:203]
	v_pk_add_f32 v[82:83], v[82:83], v[202:203]
	v_pk_add_f32 v[84:85], v[84:85], v[202:203]
	v_pk_add_f32 v[86:87], v[86:87], v[202:203]
	v_pk_add_f32 v[88:89], v[88:89], v[202:203]
	v_pk_add_f32 v[90:91], v[90:91], v[202:203]
	v_pk_add_f32 v[92:93], v[92:93], v[202:203]
	v_pk_add_f32 v[94:95], v[94:95], v[202:203]
	v_pk_add_f32 v[96:97], v[96:97], v[202:203]
	v_exp_f32_e32 v66, v66
	v_exp_f32_e32 v67, v67
	v_exp_f32_e32 v68, v68
	v_exp_f32_e32 v69, v69
	v_exp_f32_e32 v70, v70
	v_exp_f32_e32 v71, v71
	v_exp_f32_e32 v72, v72
	v_exp_f32_e32 v73, v73
	v_exp_f32_e32 v74, v74
	v_exp_f32_e32 v75, v75
	v_exp_f32_e32 v76, v76
	v_exp_f32_e32 v77, v77
	v_exp_f32_e32 v78, v78
	v_exp_f32_e32 v79, v79
	v_exp_f32_e32 v80, v80
	v_exp_f32_e32 v81, v81
	v_exp_f32_e32 v82, v82
	v_exp_f32_e32 v83, v83
	v_exp_f32_e32 v84, v84
	v_exp_f32_e32 v85, v85
	v_exp_f32_e32 v86, v86
	v_exp_f32_e32 v87, v87
	v_exp_f32_e32 v88, v88
	v_exp_f32_e32 v89, v89
	v_exp_f32_e32 v90, v90
	v_exp_f32_e32 v91, v91
	v_exp_f32_e32 v92, v92
	v_exp_f32_e32 v93, v93
	v_exp_f32_e32 v94, v94
	v_exp_f32_e32 v95, v95
	v_exp_f32_e32 v96, v96
	v_exp_f32_e32 v97, v97
	v_pk_add_f32 v[212:213], v[98:99], v[100:101]
	v_pk_add_f32 v[214:215], v[102:103], v[104:105]
	v_pk_add_f32 v[212:213], v[212:213], v[106:107]
	v_pk_add_f32 v[214:215], v[214:215], v[108:109]
	v_pk_add_f32 v[212:213], v[212:213], v[110:111]
	v_pk_add_f32 v[214:215], v[214:215], v[112:113]
	v_pk_add_f32 v[212:213], v[212:213], v[114:115]
	v_pk_add_f32 v[214:215], v[214:215], v[116:117]
	v_pk_add_f32 v[212:213], v[212:213], v[118:119]
	v_pk_add_f32 v[214:215], v[214:215], v[120:121]
	v_pk_add_f32 v[212:213], v[212:213], v[122:123]
	v_pk_add_f32 v[214:215], v[214:215], v[124:125]
	v_pk_add_f32 v[212:213], v[212:213], v[126:127]
	v_pk_add_f32 v[214:215], v[214:215], v[128:129]
	v_pk_add_f32 v[212:213], v[212:213], v[214:215]
	v_add_f32_e32 v210, v212, v213
	ds_bpermute_b32 v211, v249, v210
	v_pk_add_f32 v[220:221], v[66:67], v[68:69]
	v_pk_add_f32 v[222:223], v[70:71], v[72:73]
	v_pk_add_f32 v[220:221], v[220:221], v[74:75]
	v_pk_add_f32 v[222:223], v[222:223], v[76:77]
	v_pk_add_f32 v[220:221], v[220:221], v[78:79]
	v_pk_add_f32 v[222:223], v[222:223], v[80:81]
	v_pk_add_f32 v[220:221], v[220:221], v[82:83]
	v_pk_add_f32 v[222:223], v[222:223], v[84:85]
	v_pk_add_f32 v[220:221], v[220:221], v[86:87]
	v_pk_add_f32 v[222:223], v[222:223], v[88:89]
	v_pk_add_f32 v[220:221], v[220:221], v[90:91]
	v_pk_add_f32 v[222:223], v[222:223], v[92:93]
	v_pk_add_f32 v[220:221], v[220:221], v[94:95]
	v_pk_add_f32 v[222:223], v[222:223], v[96:97]
	v_pk_add_f32 v[220:221], v[220:221], v[222:223]
	v_add_f32_e32 v224, v220, v221
	ds_bpermute_b32 v225, v249, v224
	v_cmp_neq_f32_e32 vcc, 1.0, v226
	s_cbranch_vccz .Lattn_far_p_sa
	v_mov_b32_e32 v227, v226
	v_pk_mul_f32 v[64:65], v[64:65], v[226:227]
	v_pk_mul_f32 v[62:63], v[62:63], v[226:227]
	v_pk_mul_f32 v[60:61], v[60:61], v[226:227]
	v_pk_mul_f32 v[58:59], v[58:59], v[226:227]
	v_pk_mul_f32 v[56:57], v[56:57], v[226:227]
	v_pk_mul_f32 v[54:55], v[54:55], v[226:227]
	v_pk_mul_f32 v[52:53], v[52:53], v[226:227]
	v_pk_mul_f32 v[50:51], v[50:51], v[226:227]
	v_pk_mul_f32 v[48:49], v[48:49], v[226:227]
	v_pk_mul_f32 v[46:47], v[46:47], v[226:227]
	v_pk_mul_f32 v[44:45], v[44:45], v[226:227]
	v_pk_mul_f32 v[42:43], v[42:43], v[226:227]
	v_pk_mul_f32 v[40:41], v[40:41], v[226:227]
	v_pk_mul_f32 v[38:39], v[38:39], v[226:227]
	v_pk_mul_f32 v[36:37], v[36:37], v[226:227]
	v_pk_mul_f32 v[34:35], v[34:35], v[226:227]

.Lattn_far_p_sb:
	v_cvt_pk_bf16_f32 v98, v98, v99
	v_cvt_pk_bf16_f32 v99, v100, v101
	v_cvt_pk_bf16_f32 v100, v102, v103
	v_cvt_pk_bf16_f32 v101, v104, v105
	v_cvt_pk_bf16_f32 v66, v66, v67
	v_cvt_pk_bf16_f32 v67, v68, v69
	v_cvt_pk_bf16_f32 v68, v70, v71
	v_cvt_pk_bf16_f32 v69, v72, v73
	s_waitcnt vmcnt(7)
	v_mfma_f32_32x32x16_bf16 v[50:65], v[158:161], v[98:101], v[50:65]
	v_cvt_pk_bf16_f32 v102, v106, v107
	v_cvt_pk_bf16_f32 v103, v108, v109
	v_cvt_pk_bf16_f32 v104, v110, v111
	v_cvt_pk_bf16_f32 v105, v112, v113
	v_mfma_f32_32x32x16_bf16 v[18:33], v[158:161], v[66:69], v[18:33]
	v_cvt_pk_bf16_f32 v70, v74, v75
	v_cvt_pk_bf16_f32 v71, v76, v77
	v_cvt_pk_bf16_f32 v72, v78, v79
	v_cvt_pk_bf16_f32 v73, v80, v81
	s_waitcnt vmcnt(6)
	v_mfma_f32_32x32x16_bf16 v[34:49], v[154:157], v[98:101], v[34:49]
	v_mfma_f32_32x32x16_bf16 v[2:17], v[154:157], v[66:69], v[2:17]
	v_cvt_pk_bf16_f32 v106, v114, v115
	v_cvt_pk_bf16_f32 v107, v116, v117
	v_cvt_pk_bf16_f32 v108, v118, v119
	v_cvt_pk_bf16_f32 v109, v120, v121
	v_cvt_pk_bf16_f32 v74, v82, v83
	v_cvt_pk_bf16_f32 v75, v84, v85
	v_cvt_pk_bf16_f32 v76, v86, v87
	v_cvt_pk_bf16_f32 v77, v88, v89
	s_waitcnt vmcnt(5)
	v_mfma_f32_32x32x16_bf16 v[50:65], v[150:153], v[102:105], v[50:65]
	v_mfma_f32_32x32x16_bf16 v[18:33], v[150:153], v[70:73], v[18:33]
	s_waitcnt vmcnt(4)
	v_mfma_f32_32x32x16_bf16 v[34:49], v[146:149], v[102:105], v[34:49]
	v_mfma_f32_32x32x16_bf16 v[2:17], v[146:149], v[70:73], v[2:17]
	v_cvt_pk_bf16_f32 v110, v122, v123
	v_cvt_pk_bf16_f32 v111, v124, v125
	v_cvt_pk_bf16_f32 v112, v126, v127
	v_cvt_pk_bf16_f32 v113, v128, v129
	v_cvt_pk_bf16_f32 v78, v90, v91
	v_cvt_pk_bf16_f32 v79, v92, v93
	v_cvt_pk_bf16_f32 v80, v94, v95
	v_cvt_pk_bf16_f32 v81, v96, v97
	s_waitcnt vmcnt(3)
	v_mfma_f32_32x32x16_bf16 v[50:65], v[138:141], v[106:109], v[50:65]
	v_mfma_f32_32x32x16_bf16 v[18:33], v[138:141], v[74:77], v[18:33]
	s_waitcnt vmcnt(1)
	v_mfma_f32_32x32x16_bf16 v[34:49], v[142:145], v[106:109], v[34:49]
	v_mfma_f32_32x32x16_bf16 v[2:17], v[142:145], v[74:77], v[2:17]
	v_mfma_f32_32x32x16_bf16 v[50:65], v[134:137], v[110:113], v[50:65]
	v_mfma_f32_32x32x16_bf16 v[18:33], v[134:137], v[78:81], v[18:33]
	s_waitcnt lgkmcnt(0)
	v_add_f32_e32 v210, v210, v211
	v_add_f32_e32 v224, v224, v225
	v_fma_f32 v176, v176, v226, v210
	v_fma_f32 v175, v175, v228, v224
	v_lshl_add_u64 v[168:169], v[168:169], 0, s[84:85]
	v_lshl_add_u64 v[170:171], v[170:171], 0, s[84:85]
	s_waitcnt vmcnt(0)
	v_mfma_f32_32x32x16_bf16 v[34:49], v[130:133], v[110:113], v[34:49]
	v_mfma_f32_32x32x16_bf16 v[2:17], v[130:133], v[78:81], v[2:17]
	v_mov_b32_e32 v189, v218
	v_mov_b32_e32 v199, v236
	s_cmp_gt_u32 s9, 7
	s_cbranch_scc0 .LBB0_1432
	v_mov_b32_e32 v66, v176
	v_mov_b32_e32 v86, v175
	v_mov_b32_e32 v99, v249
